# FFN-in K-loop: leading wave half runs its own loop copy with the counted LDS-DMA waits one slot later
# speedup vs baseline: 1.0062x; 1.0062x over previous
.LBB0_663:
	s_ashr_i32 s61, s60, 31
	s_lshl_b64 s[10:11], s[60:61], 19
	s_add_u32 s62, s21, s10
	s_addc_u32 s63, s24, s11
	s_and_b64 s[10:11], s[12:13], exec
	s_cselect_b32 s10, s63, s69
	s_cselect_b32 s11, s62, s68
	s_ashr_i32 s59, s58, 31
	s_lshl_b64 s[64:65], s[58:59], 19
	s_add_u32 s64, s27, s64
	s_addc_u32 s65, s34, s65
	s_and_b64 s[72:73], s[12:13], exec
	s_cselect_b32 s15, s65, s71
	s_cselect_b32 s59, s64, s70
	s_add_u32 s68, s68, 0x40080
	s_addc_u32 s69, s69, 0
	s_add_u32 s61, s70, 0x100
	s_addc_u32 s67, s71, 0
	s_mov_b32 s80, -2
	s_and_b64 vcc, exec, s[18:19]
	s_cbranch_vccnz .Llw4_lead
	s_add_u32 s6, s68, 0xfffc0080
	s_addc_u32 s33, s69, -1
	s_add_i32 s82, 0, 0x10000
	s_cmp_eq_u32 s80, 12
	s_cselect_b32 s73, s10, s33
	s_cselect_b32 s72, s11, s6
	v_add_u32_e32 v2, s82, v148
	s_cselect_b32 s71, s15, s67
	s_cselect_b32 s70, s59, s61
	s_add_i32 s6, 0, 0x14000
	ds_read_b128 v[152:155], v2
	ds_read_b128 v[156:159], v2 offset:1024
	ds_read_b128 v[160:163], v2 offset:2048
	ds_read_b128 v[168:171], v2 offset:3072
	v_add_u32_e32 v2, s6, v148
	ds_read_b128 v[174:177], v2
	ds_read_b128 v[178:181], v2 offset:1024
	ds_read_b128 v[182:185], v2 offset:2048
	ds_read_b128 v[186:189], v2 offset:3072
	v_lshl_add_u64 v[146:147], s[68:69], 0, v[142:143]
	s_add_i32 m0, s35, 0xc000
	ds_read_b128 v[200:203], v151
	ds_read_b128 v[204:207], v151 offset:1024
	ds_read_b128 v[208:211], v151 offset:2048
	ds_read_b128 v[212:215], v151 offset:3072
	ds_read_b128 v[216:219], v151 offset:4096
	ds_read_b128 v[220:223], v151 offset:5120
	ds_read_b128 v[224:227], v151 offset:6144
	ds_read_b128 v[228:231], v151 offset:7168
	global_load_lds_dwordx4 v[146:147], off
	v_lshl_add_u64 v[146:147], s[68:69], 0, v[144:145]
	s_add_i32 m0, s35, 0xe000
	s_nop 0
	global_load_lds_dwordx4 v[146:147], off
	s_waitcnt vmcnt(8)
	s_waitcnt lgkmcnt(0)
	s_barrier
	s_waitcnt lgkmcnt(0)
	v_mfma_f32_16x16x32_bf16 v[128:131], v[152:155], v[200:203], 0
	v_mfma_f32_16x16x32_bf16 v[120:123], v[160:163], v[200:203], 0
	v_mfma_f32_16x16x32_bf16 v[112:115], v[152:155], v[208:211], 0
	v_mfma_f32_16x16x32_bf16 v[104:107], v[160:163], v[208:211], 0
	v_mfma_f32_16x16x32_bf16 v[96:99], v[152:155], v[216:219], 0
	v_mfma_f32_16x16x32_bf16 v[88:91], v[160:163], v[216:219], 0
	v_mfma_f32_16x16x32_bf16 v[80:83], v[152:155], v[224:227], 0
	v_mfma_f32_16x16x32_bf16 v[72:75], v[160:163], v[224:227], 0
	v_mfma_f32_16x16x32_bf16 v[128:131], v[156:159], v[204:207], v[128:131]
	v_mfma_f32_16x16x32_bf16 v[120:123], v[168:171], v[204:207], v[120:123]
	v_mfma_f32_16x16x32_bf16 v[112:115], v[156:159], v[212:215], v[112:115]
	v_mfma_f32_16x16x32_bf16 v[104:107], v[168:171], v[212:215], v[104:107]
	v_mfma_f32_16x16x32_bf16 v[96:99], v[156:159], v[220:223], v[96:99]
	v_mfma_f32_16x16x32_bf16 v[88:91], v[168:171], v[220:223], v[88:91]
	v_mfma_f32_16x16x32_bf16 v[80:83], v[156:159], v[228:231], v[80:83]
	v_mfma_f32_16x16x32_bf16 v[72:75], v[168:171], v[228:231], v[72:75]
	v_mfma_f32_16x16x32_bf16 v[124:127], v[174:177], v[200:203], 0
	v_mfma_f32_16x16x32_bf16 v[116:119], v[182:185], v[200:203], 0
	v_mfma_f32_16x16x32_bf16 v[108:111], v[174:177], v[208:211], 0
	v_mfma_f32_16x16x32_bf16 v[100:103], v[182:185], v[208:211], 0
	v_mfma_f32_16x16x32_bf16 v[92:95], v[174:177], v[216:219], 0
	v_mfma_f32_16x16x32_bf16 v[84:87], v[182:185], v[216:219], 0
	v_mfma_f32_16x16x32_bf16 v[76:79], v[174:177], v[224:227], 0
	v_mfma_f32_16x16x32_bf16 v[68:71], v[182:185], v[224:227], 0
	v_mfma_f32_16x16x32_bf16 v[124:127], v[178:181], v[204:207], v[124:127]
	v_mfma_f32_16x16x32_bf16 v[116:119], v[186:189], v[204:207], v[116:119]
	v_mfma_f32_16x16x32_bf16 v[108:111], v[178:181], v[212:215], v[108:111]
	v_mfma_f32_16x16x32_bf16 v[100:103], v[186:189], v[212:215], v[100:103]
	v_mfma_f32_16x16x32_bf16 v[92:95], v[178:181], v[220:223], v[92:95]
	v_mfma_f32_16x16x32_bf16 v[84:87], v[186:189], v[220:223], v[84:87]
	v_mfma_f32_16x16x32_bf16 v[76:79], v[178:181], v[228:231], v[76:79]
	v_mfma_f32_16x16x32_bf16 v[68:71], v[186:189], v[228:231], v[68:71]
	s_barrier
	s_add_i32 s33, s82, s20
	v_lshl_add_u64 v[146:147], s[70:71], 0, v[134:135]
	s_mov_b32 m0, s33
	ds_read_b128 v[200:203], v151 offset:16384
	ds_read_b128 v[204:207], v151 offset:17408
	ds_read_b128 v[208:211], v151 offset:18432
	ds_read_b128 v[212:215], v151 offset:19456
	ds_read_b128 v[216:219], v151 offset:20480
	ds_read_b128 v[220:223], v151 offset:21504
	ds_read_b128 v[224:227], v151 offset:22528
	ds_read_b128 v[228:231], v151 offset:23552
	global_load_lds_dwordx4 v[146:147], off
	s_add_i32 m0, s33, 0x2000
	s_add_u32 s82, s70, 0x40000
	v_lshl_add_u64 v[164:165], s[70:71], 0, v[138:139]
	s_addc_u32 s83, s71, 0
	s_add_i32 s6, s6, s20
	global_load_lds_dwordx4 v[164:165], off
	v_lshl_add_u64 v[232:233], s[82:83], 0, v[134:135]
	s_mov_b32 m0, s6
	v_lshl_add_u64 v[234:235], s[72:73], 0, v[136:137]
	global_load_lds_dwordx4 v[232:233], off
	v_lshl_add_u64 v[232:233], s[82:83], 0, v[138:139]
	s_add_i32 m0, s6, 0x2000
	s_nop 0
	global_load_lds_dwordx4 v[232:233], off
	v_lshl_add_u64 v[232:233], s[72:73], 0, v[132:133]
	s_mov_b32 m0, s35
	s_nop 0
	global_load_lds_dwordx4 v[232:233], off
	s_mov_b32 m0, s54
	s_nop 0
	global_load_lds_dwordx4 v[234:235], off
	s_waitcnt vmcnt(8)
	s_waitcnt lgkmcnt(0)
	s_barrier
	s_waitcnt lgkmcnt(0)
	v_mfma_f32_16x16x32_bf16 v[64:67], v[152:155], v[200:203], 0
	v_mfma_f32_16x16x32_bf16 v[56:59], v[160:163], v[200:203], 0
	v_mfma_f32_16x16x32_bf16 v[48:51], v[152:155], v[208:211], 0
	v_mfma_f32_16x16x32_bf16 v[40:43], v[160:163], v[208:211], 0
	v_mfma_f32_16x16x32_bf16 v[32:35], v[152:155], v[216:219], 0
	v_mfma_f32_16x16x32_bf16 v[24:27], v[160:163], v[216:219], 0
	v_mfma_f32_16x16x32_bf16 v[16:19], v[152:155], v[224:227], 0
	v_mfma_f32_16x16x32_bf16 v[8:11], v[160:163], v[224:227], 0
	v_mfma_f32_16x16x32_bf16 v[64:67], v[156:159], v[204:207], v[64:67]
	v_mfma_f32_16x16x32_bf16 v[56:59], v[168:171], v[204:207], v[56:59]
	v_mfma_f32_16x16x32_bf16 v[48:51], v[156:159], v[212:215], v[48:51]
	v_mfma_f32_16x16x32_bf16 v[40:43], v[168:171], v[212:215], v[40:43]
	v_mfma_f32_16x16x32_bf16 v[32:35], v[156:159], v[220:223], v[32:35]
	v_mfma_f32_16x16x32_bf16 v[24:27], v[168:171], v[220:223], v[24:27]
	v_mfma_f32_16x16x32_bf16 v[16:19], v[156:159], v[228:231], v[16:19]
	v_mfma_f32_16x16x32_bf16 v[8:11], v[168:171], v[228:231], v[8:11]
	v_mfma_f32_16x16x32_bf16 v[60:63], v[174:177], v[200:203], 0
	v_mfma_f32_16x16x32_bf16 v[52:55], v[182:185], v[200:203], 0
	v_mfma_f32_16x16x32_bf16 v[44:47], v[174:177], v[208:211], 0
	v_mfma_f32_16x16x32_bf16 v[36:39], v[182:185], v[208:211], 0
	v_mfma_f32_16x16x32_bf16 v[28:31], v[174:177], v[216:219], 0
	v_mfma_f32_16x16x32_bf16 v[20:23], v[182:185], v[216:219], 0
	v_mfma_f32_16x16x32_bf16 v[12:15], v[174:177], v[224:227], 0
	v_mfma_f32_16x16x32_bf16 v[4:7], v[182:185], v[224:227], 0
	v_mfma_f32_16x16x32_bf16 v[60:63], v[178:181], v[204:207], v[60:63]
	v_mfma_f32_16x16x32_bf16 v[52:55], v[186:189], v[204:207], v[52:55]
	v_mfma_f32_16x16x32_bf16 v[44:47], v[178:181], v[212:215], v[44:47]
	v_mfma_f32_16x16x32_bf16 v[36:39], v[186:189], v[212:215], v[36:39]
	v_mfma_f32_16x16x32_bf16 v[28:31], v[178:181], v[220:223], v[28:31]
	v_mfma_f32_16x16x32_bf16 v[20:23], v[186:189], v[220:223], v[20:23]
	v_mfma_f32_16x16x32_bf16 v[12:15], v[178:181], v[228:231], v[12:15]
	v_mfma_f32_16x16x32_bf16 v[4:7], v[186:189], v[228:231], v[4:7]
	s_barrier
	s_add_i32 s6, 0, 0x18000
	v_add_u32_e32 v2, s6, v148
	s_add_i32 s33, 0, 0x1c000
	ds_read_b128 v[152:155], v2
	ds_read_b128 v[156:159], v2 offset:1024
	ds_read_b128 v[160:163], v2 offset:2048
	ds_read_b128 v[168:171], v2 offset:3072
	v_add_u32_e32 v2, s33, v148
	ds_read_b128 v[174:177], v2
	ds_read_b128 v[178:181], v2 offset:1024
	ds_read_b128 v[182:185], v2 offset:2048
	ds_read_b128 v[186:189], v2 offset:3072
	s_add_u32 s72, s72, 0x40000
	s_addc_u32 s73, s73, 0
	s_mov_b32 m0, s55
	v_lshl_add_u64 v[236:237], s[72:73], 0, v[132:133]
	ds_read_b128 v[200:203], v151 offset:32768
	ds_read_b128 v[204:207], v151 offset:33792
	ds_read_b128 v[208:211], v151 offset:34816
	ds_read_b128 v[212:215], v151 offset:35840
	ds_read_b128 v[216:219], v151 offset:36864
	ds_read_b128 v[220:223], v151 offset:37888
	ds_read_b128 v[224:227], v151 offset:38912
	ds_read_b128 v[228:231], v151 offset:39936
	global_load_lds_dwordx4 v[236:237], off
	v_lshl_add_u64 v[236:237], s[72:73], 0, v[136:137]
	s_mov_b32 m0, s56
	s_nop 0
	global_load_lds_dwordx4 v[236:237], off
	s_waitcnt vmcnt(8)
	s_waitcnt lgkmcnt(0)
	s_barrier
	s_waitcnt lgkmcnt(0)
	v_mfma_f32_16x16x32_bf16 v[128:131], v[152:155], v[200:203], v[128:131]
	v_mfma_f32_16x16x32_bf16 v[120:123], v[160:163], v[200:203], v[120:123]
	v_mfma_f32_16x16x32_bf16 v[112:115], v[152:155], v[208:211], v[112:115]
	v_mfma_f32_16x16x32_bf16 v[104:107], v[160:163], v[208:211], v[104:107]
	v_mfma_f32_16x16x32_bf16 v[96:99], v[152:155], v[216:219], v[96:99]
	v_mfma_f32_16x16x32_bf16 v[88:91], v[160:163], v[216:219], v[88:91]
	v_mfma_f32_16x16x32_bf16 v[80:83], v[152:155], v[224:227], v[80:83]
	v_mfma_f32_16x16x32_bf16 v[72:75], v[160:163], v[224:227], v[72:75]
	v_mfma_f32_16x16x32_bf16 v[128:131], v[156:159], v[204:207], v[128:131]
	v_mfma_f32_16x16x32_bf16 v[120:123], v[168:171], v[204:207], v[120:123]
	v_mfma_f32_16x16x32_bf16 v[112:115], v[156:159], v[212:215], v[112:115]
	v_mfma_f32_16x16x32_bf16 v[104:107], v[168:171], v[212:215], v[104:107]
	v_mfma_f32_16x16x32_bf16 v[96:99], v[156:159], v[220:223], v[96:99]
	v_mfma_f32_16x16x32_bf16 v[88:91], v[168:171], v[220:223], v[88:91]
	v_mfma_f32_16x16x32_bf16 v[80:83], v[156:159], v[228:231], v[80:83]
	v_mfma_f32_16x16x32_bf16 v[72:75], v[168:171], v[228:231], v[72:75]
	v_mfma_f32_16x16x32_bf16 v[124:127], v[174:177], v[200:203], v[124:127]
	v_mfma_f32_16x16x32_bf16 v[116:119], v[182:185], v[200:203], v[116:119]
	v_mfma_f32_16x16x32_bf16 v[108:111], v[174:177], v[208:211], v[108:111]
	v_mfma_f32_16x16x32_bf16 v[100:103], v[182:185], v[208:211], v[100:103]
	v_mfma_f32_16x16x32_bf16 v[92:95], v[174:177], v[216:219], v[92:95]
	v_mfma_f32_16x16x32_bf16 v[84:87], v[182:185], v[216:219], v[84:87]
	v_mfma_f32_16x16x32_bf16 v[76:79], v[174:177], v[224:227], v[76:79]
	v_mfma_f32_16x16x32_bf16 v[68:71], v[182:185], v[224:227], v[68:71]
	v_mfma_f32_16x16x32_bf16 v[124:127], v[178:181], v[204:207], v[124:127]
	v_mfma_f32_16x16x32_bf16 v[116:119], v[186:189], v[204:207], v[116:119]
	v_mfma_f32_16x16x32_bf16 v[108:111], v[178:181], v[212:215], v[108:111]
	v_mfma_f32_16x16x32_bf16 v[100:103], v[186:189], v[212:215], v[100:103]
	v_mfma_f32_16x16x32_bf16 v[92:95], v[178:181], v[220:223], v[92:95]
	v_mfma_f32_16x16x32_bf16 v[84:87], v[186:189], v[220:223], v[84:87]
	v_mfma_f32_16x16x32_bf16 v[76:79], v[178:181], v[228:231], v[76:79]
	v_mfma_f32_16x16x32_bf16 v[68:71], v[186:189], v[228:231], v[68:71]
	s_barrier
	s_add_i32 s6, s6, s20
	v_lshl_add_u64 v[146:147], v[146:147], 0, s[30:31]
	s_mov_b32 m0, s6
	ds_read_b128 v[200:203], v151 offset:49152
	ds_read_b128 v[204:207], v151 offset:50176
	ds_read_b128 v[208:211], v151 offset:51200
	ds_read_b128 v[212:215], v151 offset:52224
	ds_read_b128 v[216:219], v151 offset:53248
	ds_read_b128 v[220:223], v151 offset:54272
	ds_read_b128 v[224:227], v151 offset:55296
	ds_read_b128 v[228:231], v151 offset:56320
	global_load_lds_dwordx4 v[146:147], off
	s_add_i32 m0, s6, 0x2000
	s_add_u32 s70, s70, 0x40080
	v_lshl_add_u64 v[146:147], v[164:165], 0, s[30:31]
	s_addc_u32 s71, s71, 0
	s_add_i32 s6, s33, s20
	global_load_lds_dwordx4 v[146:147], off
	v_lshl_add_u64 v[146:147], s[70:71], 0, v[134:135]
	s_mov_b32 m0, s6
	s_nop 0
	global_load_lds_dwordx4 v[146:147], off
	v_lshl_add_u64 v[146:147], s[70:71], 0, v[138:139]
	s_add_i32 m0, s6, 0x2000
	s_nop 0
	global_load_lds_dwordx4 v[146:147], off
	v_lshl_add_u64 v[146:147], v[232:233], 0, s[30:31]
	s_mov_b32 m0, s76
	s_nop 0
	global_load_lds_dwordx4 v[146:147], off
	v_lshl_add_u64 v[146:147], v[234:235], 0, s[30:31]
	s_mov_b32 m0, s77
	s_nop 0
	global_load_lds_dwordx4 v[146:147], off
	s_waitcnt vmcnt(8)
	s_waitcnt lgkmcnt(0)
	s_barrier
	s_waitcnt lgkmcnt(0)
	v_mfma_f32_16x16x32_bf16 v[64:67], v[152:155], v[200:203], v[64:67]
	v_mfma_f32_16x16x32_bf16 v[56:59], v[160:163], v[200:203], v[56:59]
	v_mfma_f32_16x16x32_bf16 v[48:51], v[152:155], v[208:211], v[48:51]
	v_mfma_f32_16x16x32_bf16 v[40:43], v[160:163], v[208:211], v[40:43]
	v_mfma_f32_16x16x32_bf16 v[32:35], v[152:155], v[216:219], v[32:35]
	v_mfma_f32_16x16x32_bf16 v[24:27], v[160:163], v[216:219], v[24:27]
	v_mfma_f32_16x16x32_bf16 v[16:19], v[152:155], v[224:227], v[16:19]
	v_mfma_f32_16x16x32_bf16 v[8:11], v[160:163], v[224:227], v[8:11]
	v_mfma_f32_16x16x32_bf16 v[64:67], v[156:159], v[204:207], v[64:67]
	v_mfma_f32_16x16x32_bf16 v[56:59], v[168:171], v[204:207], v[56:59]
	v_mfma_f32_16x16x32_bf16 v[48:51], v[156:159], v[212:215], v[48:51]
	v_mfma_f32_16x16x32_bf16 v[40:43], v[168:171], v[212:215], v[40:43]
	v_mfma_f32_16x16x32_bf16 v[32:35], v[156:159], v[220:223], v[32:35]
	v_mfma_f32_16x16x32_bf16 v[24:27], v[168:171], v[220:223], v[24:27]
	v_mfma_f32_16x16x32_bf16 v[16:19], v[156:159], v[228:231], v[16:19]
	v_mfma_f32_16x16x32_bf16 v[8:11], v[168:171], v[228:231], v[8:11]
	v_mfma_f32_16x16x32_bf16 v[60:63], v[174:177], v[200:203], v[60:63]
	v_mfma_f32_16x16x32_bf16 v[52:55], v[182:185], v[200:203], v[52:55]
	v_mfma_f32_16x16x32_bf16 v[44:47], v[174:177], v[208:211], v[44:47]
	v_mfma_f32_16x16x32_bf16 v[36:39], v[182:185], v[208:211], v[36:39]
	v_mfma_f32_16x16x32_bf16 v[28:31], v[174:177], v[216:219], v[28:31]
	v_mfma_f32_16x16x32_bf16 v[20:23], v[182:185], v[216:219], v[20:23]
	v_mfma_f32_16x16x32_bf16 v[12:15], v[174:177], v[224:227], v[12:15]
	v_mfma_f32_16x16x32_bf16 v[4:7], v[182:185], v[224:227], v[4:7]
	v_mfma_f32_16x16x32_bf16 v[60:63], v[178:181], v[204:207], v[60:63]
	v_mfma_f32_16x16x32_bf16 v[52:55], v[186:189], v[204:207], v[52:55]
	v_mfma_f32_16x16x32_bf16 v[44:47], v[178:181], v[212:215], v[44:47]
	v_mfma_f32_16x16x32_bf16 v[36:39], v[186:189], v[212:215], v[36:39]
	v_mfma_f32_16x16x32_bf16 v[28:31], v[178:181], v[220:223], v[28:31]
	v_mfma_f32_16x16x32_bf16 v[20:23], v[186:189], v[220:223], v[20:23]
	v_mfma_f32_16x16x32_bf16 v[12:15], v[178:181], v[228:231], v[12:15]
	v_mfma_f32_16x16x32_bf16 v[4:7], v[186:189], v[228:231], v[4:7]
	s_barrier
	s_add_i32 s80, s80, 2
	s_add_u32 s68, s68, 0x100
	s_addc_u32 s69, s69, 0
	s_add_u32 s61, s61, 0x100
	s_addc_u32 s67, s67, 0
.LBB0_664:
	s_add_u32 s6, s68, 0xfffc0080
	s_addc_u32 s33, s69, -1
	s_add_i32 s82, 0, 0x10000
	s_cmp_eq_u32 s80, 12
	s_cselect_b32 s73, s10, s33
	s_cselect_b32 s72, s11, s6
	v_add_u32_e32 v2, s82, v148
	s_cselect_b32 s71, s15, s67
	s_cselect_b32 s70, s59, s61
	s_add_i32 s6, 0, 0x14000
	ds_read_b128 v[152:155], v2
	ds_read_b128 v[156:159], v2 offset:1024
	ds_read_b128 v[160:163], v2 offset:2048
	ds_read_b128 v[168:171], v2 offset:3072
	v_add_u32_e32 v2, s6, v148
	ds_read_b128 v[174:177], v2
	ds_read_b128 v[178:181], v2 offset:1024
	ds_read_b128 v[182:185], v2 offset:2048
	ds_read_b128 v[186:189], v2 offset:3072
	v_lshl_add_u64 v[146:147], s[68:69], 0, v[142:143]
	s_add_i32 m0, s35, 0xc000
	ds_read_b128 v[200:203], v151
	ds_read_b128 v[204:207], v151 offset:1024
	ds_read_b128 v[208:211], v151 offset:2048
	ds_read_b128 v[212:215], v151 offset:3072
	ds_read_b128 v[216:219], v151 offset:4096
	ds_read_b128 v[220:223], v151 offset:5120
	ds_read_b128 v[224:227], v151 offset:6144
	ds_read_b128 v[228:231], v151 offset:7168
	global_load_lds_dwordx4 v[146:147], off
	v_lshl_add_u64 v[146:147], s[68:69], 0, v[144:145]
	s_add_i32 m0, s35, 0xe000
	s_nop 0
	global_load_lds_dwordx4 v[146:147], off
	s_waitcnt vmcnt(8)
	s_waitcnt lgkmcnt(0)
	s_barrier
	s_waitcnt lgkmcnt(0)
	v_mfma_f32_16x16x32_bf16 v[128:131], v[152:155], v[200:203], v[128:131]
	v_mfma_f32_16x16x32_bf16 v[120:123], v[160:163], v[200:203], v[120:123]
	v_mfma_f32_16x16x32_bf16 v[112:115], v[152:155], v[208:211], v[112:115]
	v_mfma_f32_16x16x32_bf16 v[104:107], v[160:163], v[208:211], v[104:107]
	v_mfma_f32_16x16x32_bf16 v[96:99], v[152:155], v[216:219], v[96:99]
	v_mfma_f32_16x16x32_bf16 v[88:91], v[160:163], v[216:219], v[88:91]
	v_mfma_f32_16x16x32_bf16 v[80:83], v[152:155], v[224:227], v[80:83]
	v_mfma_f32_16x16x32_bf16 v[72:75], v[160:163], v[224:227], v[72:75]
	v_mfma_f32_16x16x32_bf16 v[128:131], v[156:159], v[204:207], v[128:131]
	v_mfma_f32_16x16x32_bf16 v[120:123], v[168:171], v[204:207], v[120:123]
	v_mfma_f32_16x16x32_bf16 v[112:115], v[156:159], v[212:215], v[112:115]
	v_mfma_f32_16x16x32_bf16 v[104:107], v[168:171], v[212:215], v[104:107]
	v_mfma_f32_16x16x32_bf16 v[96:99], v[156:159], v[220:223], v[96:99]
	v_mfma_f32_16x16x32_bf16 v[88:91], v[168:171], v[220:223], v[88:91]
	v_mfma_f32_16x16x32_bf16 v[80:83], v[156:159], v[228:231], v[80:83]
	v_mfma_f32_16x16x32_bf16 v[72:75], v[168:171], v[228:231], v[72:75]
	v_mfma_f32_16x16x32_bf16 v[124:127], v[174:177], v[200:203], v[124:127]
	v_mfma_f32_16x16x32_bf16 v[116:119], v[182:185], v[200:203], v[116:119]
	v_mfma_f32_16x16x32_bf16 v[108:111], v[174:177], v[208:211], v[108:111]
	v_mfma_f32_16x16x32_bf16 v[100:103], v[182:185], v[208:211], v[100:103]
	v_mfma_f32_16x16x32_bf16 v[92:95], v[174:177], v[216:219], v[92:95]
	v_mfma_f32_16x16x32_bf16 v[84:87], v[182:185], v[216:219], v[84:87]
	v_mfma_f32_16x16x32_bf16 v[76:79], v[174:177], v[224:227], v[76:79]
	v_mfma_f32_16x16x32_bf16 v[68:71], v[182:185], v[224:227], v[68:71]
	v_mfma_f32_16x16x32_bf16 v[124:127], v[178:181], v[204:207], v[124:127]
	v_mfma_f32_16x16x32_bf16 v[116:119], v[186:189], v[204:207], v[116:119]
	v_mfma_f32_16x16x32_bf16 v[108:111], v[178:181], v[212:215], v[108:111]
	v_mfma_f32_16x16x32_bf16 v[100:103], v[186:189], v[212:215], v[100:103]
	v_mfma_f32_16x16x32_bf16 v[92:95], v[178:181], v[220:223], v[92:95]
	v_mfma_f32_16x16x32_bf16 v[84:87], v[186:189], v[220:223], v[84:87]
	v_mfma_f32_16x16x32_bf16 v[76:79], v[178:181], v[228:231], v[76:79]
	v_mfma_f32_16x16x32_bf16 v[68:71], v[186:189], v[228:231], v[68:71]
	s_barrier
	s_add_i32 s33, s82, s20
	v_lshl_add_u64 v[146:147], s[70:71], 0, v[134:135]
	s_mov_b32 m0, s33
	ds_read_b128 v[200:203], v151 offset:16384
	ds_read_b128 v[204:207], v151 offset:17408
	ds_read_b128 v[208:211], v151 offset:18432
	ds_read_b128 v[212:215], v151 offset:19456
	ds_read_b128 v[216:219], v151 offset:20480
	ds_read_b128 v[220:223], v151 offset:21504
	ds_read_b128 v[224:227], v151 offset:22528
	ds_read_b128 v[228:231], v151 offset:23552
	global_load_lds_dwordx4 v[146:147], off
	s_add_i32 m0, s33, 0x2000
	s_add_u32 s82, s70, 0x40000
	v_lshl_add_u64 v[164:165], s[70:71], 0, v[138:139]
	s_addc_u32 s83, s71, 0
	s_add_i32 s6, s6, s20
	global_load_lds_dwordx4 v[164:165], off
	v_lshl_add_u64 v[232:233], s[82:83], 0, v[134:135]
	s_mov_b32 m0, s6
	v_lshl_add_u64 v[234:235], s[72:73], 0, v[136:137]
	global_load_lds_dwordx4 v[232:233], off
	v_lshl_add_u64 v[232:233], s[82:83], 0, v[138:139]
	s_add_i32 m0, s6, 0x2000
	s_nop 0
	global_load_lds_dwordx4 v[232:233], off
	v_lshl_add_u64 v[232:233], s[72:73], 0, v[132:133]
	s_mov_b32 m0, s35
	s_nop 0
	global_load_lds_dwordx4 v[232:233], off
	s_mov_b32 m0, s54
	s_nop 0
	global_load_lds_dwordx4 v[234:235], off
	s_waitcnt vmcnt(8)
	s_waitcnt lgkmcnt(0)
	s_barrier
	s_waitcnt lgkmcnt(0)
	v_mfma_f32_16x16x32_bf16 v[64:67], v[152:155], v[200:203], v[64:67]
	v_mfma_f32_16x16x32_bf16 v[56:59], v[160:163], v[200:203], v[56:59]
	v_mfma_f32_16x16x32_bf16 v[48:51], v[152:155], v[208:211], v[48:51]
	v_mfma_f32_16x16x32_bf16 v[40:43], v[160:163], v[208:211], v[40:43]
	v_mfma_f32_16x16x32_bf16 v[32:35], v[152:155], v[216:219], v[32:35]
	v_mfma_f32_16x16x32_bf16 v[24:27], v[160:163], v[216:219], v[24:27]
	v_mfma_f32_16x16x32_bf16 v[16:19], v[152:155], v[224:227], v[16:19]
	v_mfma_f32_16x16x32_bf16 v[8:11], v[160:163], v[224:227], v[8:11]
	v_mfma_f32_16x16x32_bf16 v[64:67], v[156:159], v[204:207], v[64:67]
	v_mfma_f32_16x16x32_bf16 v[56:59], v[168:171], v[204:207], v[56:59]
	v_mfma_f32_16x16x32_bf16 v[48:51], v[156:159], v[212:215], v[48:51]
	v_mfma_f32_16x16x32_bf16 v[40:43], v[168:171], v[212:215], v[40:43]
	v_mfma_f32_16x16x32_bf16 v[32:35], v[156:159], v[220:223], v[32:35]
	v_mfma_f32_16x16x32_bf16 v[24:27], v[168:171], v[220:223], v[24:27]
	v_mfma_f32_16x16x32_bf16 v[16:19], v[156:159], v[228:231], v[16:19]
	v_mfma_f32_16x16x32_bf16 v[8:11], v[168:171], v[228:231], v[8:11]
	v_mfma_f32_16x16x32_bf16 v[60:63], v[174:177], v[200:203], v[60:63]
	v_mfma_f32_16x16x32_bf16 v[52:55], v[182:185], v[200:203], v[52:55]
	v_mfma_f32_16x16x32_bf16 v[44:47], v[174:177], v[208:211], v[44:47]
	v_mfma_f32_16x16x32_bf16 v[36:39], v[182:185], v[208:211], v[36:39]
	v_mfma_f32_16x16x32_bf16 v[28:31], v[174:177], v[216:219], v[28:31]
	v_mfma_f32_16x16x32_bf16 v[20:23], v[182:185], v[216:219], v[20:23]
	v_mfma_f32_16x16x32_bf16 v[12:15], v[174:177], v[224:227], v[12:15]
	v_mfma_f32_16x16x32_bf16 v[4:7], v[182:185], v[224:227], v[4:7]
	v_mfma_f32_16x16x32_bf16 v[60:63], v[178:181], v[204:207], v[60:63]
	v_mfma_f32_16x16x32_bf16 v[52:55], v[186:189], v[204:207], v[52:55]
	v_mfma_f32_16x16x32_bf16 v[44:47], v[178:181], v[212:215], v[44:47]
	v_mfma_f32_16x16x32_bf16 v[36:39], v[186:189], v[212:215], v[36:39]
	v_mfma_f32_16x16x32_bf16 v[28:31], v[178:181], v[220:223], v[28:31]
	v_mfma_f32_16x16x32_bf16 v[20:23], v[186:189], v[220:223], v[20:23]
	v_mfma_f32_16x16x32_bf16 v[12:15], v[178:181], v[228:231], v[12:15]
	v_mfma_f32_16x16x32_bf16 v[4:7], v[186:189], v[228:231], v[4:7]
	s_barrier
	s_add_i32 s6, 0, 0x18000
	v_add_u32_e32 v2, s6, v148
	s_add_i32 s33, 0, 0x1c000
	ds_read_b128 v[152:155], v2
	ds_read_b128 v[156:159], v2 offset:1024
	ds_read_b128 v[160:163], v2 offset:2048
	ds_read_b128 v[168:171], v2 offset:3072
	v_add_u32_e32 v2, s33, v148
	ds_read_b128 v[174:177], v2
	ds_read_b128 v[178:181], v2 offset:1024
	ds_read_b128 v[182:185], v2 offset:2048
	ds_read_b128 v[186:189], v2 offset:3072
	s_add_u32 s72, s72, 0x40000
	s_addc_u32 s73, s73, 0
	s_mov_b32 m0, s55
	v_lshl_add_u64 v[236:237], s[72:73], 0, v[132:133]
	ds_read_b128 v[200:203], v151 offset:32768
	ds_read_b128 v[204:207], v151 offset:33792
	ds_read_b128 v[208:211], v151 offset:34816
	ds_read_b128 v[212:215], v151 offset:35840
	ds_read_b128 v[216:219], v151 offset:36864
	ds_read_b128 v[220:223], v151 offset:37888
	ds_read_b128 v[224:227], v151 offset:38912
	ds_read_b128 v[228:231], v151 offset:39936
	global_load_lds_dwordx4 v[236:237], off
	v_lshl_add_u64 v[236:237], s[72:73], 0, v[136:137]
	s_mov_b32 m0, s56
	s_nop 0
	global_load_lds_dwordx4 v[236:237], off
	s_waitcnt vmcnt(8)
	s_waitcnt lgkmcnt(0)
	s_barrier
	s_waitcnt lgkmcnt(0)
	v_mfma_f32_16x16x32_bf16 v[128:131], v[152:155], v[200:203], v[128:131]
	v_mfma_f32_16x16x32_bf16 v[120:123], v[160:163], v[200:203], v[120:123]
	v_mfma_f32_16x16x32_bf16 v[112:115], v[152:155], v[208:211], v[112:115]
	v_mfma_f32_16x16x32_bf16 v[104:107], v[160:163], v[208:211], v[104:107]
	v_mfma_f32_16x16x32_bf16 v[96:99], v[152:155], v[216:219], v[96:99]
	v_mfma_f32_16x16x32_bf16 v[88:91], v[160:163], v[216:219], v[88:91]
	v_mfma_f32_16x16x32_bf16 v[80:83], v[152:155], v[224:227], v[80:83]
	v_mfma_f32_16x16x32_bf16 v[72:75], v[160:163], v[224:227], v[72:75]
	v_mfma_f32_16x16x32_bf16 v[128:131], v[156:159], v[204:207], v[128:131]
	v_mfma_f32_16x16x32_bf16 v[120:123], v[168:171], v[204:207], v[120:123]
	v_mfma_f32_16x16x32_bf16 v[112:115], v[156:159], v[212:215], v[112:115]
	v_mfma_f32_16x16x32_bf16 v[104:107], v[168:171], v[212:215], v[104:107]
	v_mfma_f32_16x16x32_bf16 v[96:99], v[156:159], v[220:223], v[96:99]
	v_mfma_f32_16x16x32_bf16 v[88:91], v[168:171], v[220:223], v[88:91]
	v_mfma_f32_16x16x32_bf16 v[80:83], v[156:159], v[228:231], v[80:83]
	v_mfma_f32_16x16x32_bf16 v[72:75], v[168:171], v[228:231], v[72:75]
	v_mfma_f32_16x16x32_bf16 v[124:127], v[174:177], v[200:203], v[124:127]
	v_mfma_f32_16x16x32_bf16 v[116:119], v[182:185], v[200:203], v[116:119]
	v_mfma_f32_16x16x32_bf16 v[108:111], v[174:177], v[208:211], v[108:111]
	v_mfma_f32_16x16x32_bf16 v[100:103], v[182:185], v[208:211], v[100:103]
	v_mfma_f32_16x16x32_bf16 v[92:95], v[174:177], v[216:219], v[92:95]
	v_mfma_f32_16x16x32_bf16 v[84:87], v[182:185], v[216:219], v[84:87]
	v_mfma_f32_16x16x32_bf16 v[76:79], v[174:177], v[224:227], v[76:79]
	v_mfma_f32_16x16x32_bf16 v[68:71], v[182:185], v[224:227], v[68:71]
	v_mfma_f32_16x16x32_bf16 v[124:127], v[178:181], v[204:207], v[124:127]
	v_mfma_f32_16x16x32_bf16 v[116:119], v[186:189], v[204:207], v[116:119]
	v_mfma_f32_16x16x32_bf16 v[108:111], v[178:181], v[212:215], v[108:111]
	v_mfma_f32_16x16x32_bf16 v[100:103], v[186:189], v[212:215], v[100:103]
	v_mfma_f32_16x16x32_bf16 v[92:95], v[178:181], v[220:223], v[92:95]
	v_mfma_f32_16x16x32_bf16 v[84:87], v[186:189], v[220:223], v[84:87]
	v_mfma_f32_16x16x32_bf16 v[76:79], v[178:181], v[228:231], v[76:79]
	v_mfma_f32_16x16x32_bf16 v[68:71], v[186:189], v[228:231], v[68:71]
	s_barrier
	s_add_i32 s6, s6, s20
	v_lshl_add_u64 v[146:147], v[146:147], 0, s[30:31]
	s_mov_b32 m0, s6
	ds_read_b128 v[200:203], v151 offset:49152
	ds_read_b128 v[204:207], v151 offset:50176
	ds_read_b128 v[208:211], v151 offset:51200
	ds_read_b128 v[212:215], v151 offset:52224
	ds_read_b128 v[216:219], v151 offset:53248
	ds_read_b128 v[220:223], v151 offset:54272
	ds_read_b128 v[224:227], v151 offset:55296
	ds_read_b128 v[228:231], v151 offset:56320
	global_load_lds_dwordx4 v[146:147], off
	s_add_i32 m0, s6, 0x2000
	s_add_u32 s70, s70, 0x40080
	v_lshl_add_u64 v[146:147], v[164:165], 0, s[30:31]
	s_addc_u32 s71, s71, 0
	s_add_i32 s6, s33, s20
	global_load_lds_dwordx4 v[146:147], off
	v_lshl_add_u64 v[146:147], s[70:71], 0, v[134:135]
	s_mov_b32 m0, s6
	s_nop 0
	global_load_lds_dwordx4 v[146:147], off
	v_lshl_add_u64 v[146:147], s[70:71], 0, v[138:139]
	s_add_i32 m0, s6, 0x2000
	s_nop 0
	global_load_lds_dwordx4 v[146:147], off
	v_lshl_add_u64 v[146:147], v[232:233], 0, s[30:31]
	s_mov_b32 m0, s76
	s_nop 0
	global_load_lds_dwordx4 v[146:147], off
	v_lshl_add_u64 v[146:147], v[234:235], 0, s[30:31]
	s_mov_b32 m0, s77
	s_nop 0
	global_load_lds_dwordx4 v[146:147], off
	s_waitcnt vmcnt(8)
	s_waitcnt lgkmcnt(0)
	s_barrier
	s_waitcnt lgkmcnt(0)
	v_mfma_f32_16x16x32_bf16 v[64:67], v[152:155], v[200:203], v[64:67]
	v_mfma_f32_16x16x32_bf16 v[56:59], v[160:163], v[200:203], v[56:59]
	v_mfma_f32_16x16x32_bf16 v[48:51], v[152:155], v[208:211], v[48:51]
	v_mfma_f32_16x16x32_bf16 v[40:43], v[160:163], v[208:211], v[40:43]
	v_mfma_f32_16x16x32_bf16 v[32:35], v[152:155], v[216:219], v[32:35]
	v_mfma_f32_16x16x32_bf16 v[24:27], v[160:163], v[216:219], v[24:27]
	v_mfma_f32_16x16x32_bf16 v[16:19], v[152:155], v[224:227], v[16:19]
	v_mfma_f32_16x16x32_bf16 v[8:11], v[160:163], v[224:227], v[8:11]
	v_mfma_f32_16x16x32_bf16 v[64:67], v[156:159], v[204:207], v[64:67]
	v_mfma_f32_16x16x32_bf16 v[56:59], v[168:171], v[204:207], v[56:59]
	v_mfma_f32_16x16x32_bf16 v[48:51], v[156:159], v[212:215], v[48:51]
	v_mfma_f32_16x16x32_bf16 v[40:43], v[168:171], v[212:215], v[40:43]
	v_mfma_f32_16x16x32_bf16 v[32:35], v[156:159], v[220:223], v[32:35]
	v_mfma_f32_16x16x32_bf16 v[24:27], v[168:171], v[220:223], v[24:27]
	v_mfma_f32_16x16x32_bf16 v[16:19], v[156:159], v[228:231], v[16:19]
	v_mfma_f32_16x16x32_bf16 v[8:11], v[168:171], v[228:231], v[8:11]
	v_mfma_f32_16x16x32_bf16 v[60:63], v[174:177], v[200:203], v[60:63]
	v_mfma_f32_16x16x32_bf16 v[52:55], v[182:185], v[200:203], v[52:55]
	v_mfma_f32_16x16x32_bf16 v[44:47], v[174:177], v[208:211], v[44:47]
	v_mfma_f32_16x16x32_bf16 v[36:39], v[182:185], v[208:211], v[36:39]
	v_mfma_f32_16x16x32_bf16 v[28:31], v[174:177], v[216:219], v[28:31]
	v_mfma_f32_16x16x32_bf16 v[20:23], v[182:185], v[216:219], v[20:23]
	v_mfma_f32_16x16x32_bf16 v[12:15], v[174:177], v[224:227], v[12:15]
	v_mfma_f32_16x16x32_bf16 v[4:7], v[182:185], v[224:227], v[4:7]
	v_mfma_f32_16x16x32_bf16 v[60:63], v[178:181], v[204:207], v[60:63]
	v_mfma_f32_16x16x32_bf16 v[52:55], v[186:189], v[204:207], v[52:55]
	v_mfma_f32_16x16x32_bf16 v[44:47], v[178:181], v[212:215], v[44:47]
	v_mfma_f32_16x16x32_bf16 v[36:39], v[186:189], v[212:215], v[36:39]
	v_mfma_f32_16x16x32_bf16 v[28:31], v[178:181], v[220:223], v[28:31]
	v_mfma_f32_16x16x32_bf16 v[20:23], v[186:189], v[220:223], v[20:23]
	v_mfma_f32_16x16x32_bf16 v[12:15], v[178:181], v[228:231], v[12:15]
	v_mfma_f32_16x16x32_bf16 v[4:7], v[186:189], v[228:231], v[4:7]
	s_barrier
	s_add_i32 s80, s80, 2
	s_add_u32 s68, s68, 0x100
	s_addc_u32 s69, s69, 0
	s_add_u32 s61, s61, 0x100
	s_addc_u32 s67, s67, 0
	s_cmp_gt_u32 s80, 13
	s_cbranch_scc0 .LBB0_664
.Llw4_join:
	s_and_b64 vcc, exec, s[18:19]
	s_cbranch_vccz .LBB0_667
	s_barrier

.Llw4_lead:
	s_add_u32 s6, s68, 0xfffc0080
	s_addc_u32 s33, s69, -1
	s_add_i32 s82, 0, 0x10000
	s_cmp_eq_u32 s80, 12
	s_cselect_b32 s73, s10, s33
	s_cselect_b32 s72, s11, s6
	v_add_u32_e32 v2, s82, v148
	s_cselect_b32 s71, s15, s67
	s_cselect_b32 s70, s59, s61
	s_add_i32 s6, 0, 0x14000
	ds_read_b128 v[152:155], v2
	ds_read_b128 v[156:159], v2 offset:1024
	ds_read_b128 v[160:163], v2 offset:2048
	ds_read_b128 v[168:171], v2 offset:3072
	v_add_u32_e32 v2, s6, v148
	ds_read_b128 v[174:177], v2
	ds_read_b128 v[178:181], v2 offset:1024
	ds_read_b128 v[182:185], v2 offset:2048
	ds_read_b128 v[186:189], v2 offset:3072
	v_lshl_add_u64 v[146:147], s[68:69], 0, v[142:143]
	s_add_i32 m0, s35, 0xc000
	ds_read_b128 v[200:203], v151
	ds_read_b128 v[204:207], v151 offset:1024
	ds_read_b128 v[208:211], v151 offset:2048
	ds_read_b128 v[212:215], v151 offset:3072
	ds_read_b128 v[216:219], v151 offset:4096
	ds_read_b128 v[220:223], v151 offset:5120
	ds_read_b128 v[224:227], v151 offset:6144
	ds_read_b128 v[228:231], v151 offset:7168
	global_load_lds_dwordx4 v[146:147], off
	v_lshl_add_u64 v[146:147], s[68:69], 0, v[144:145]
	s_add_i32 m0, s35, 0xe000
	s_nop 0
	global_load_lds_dwordx4 v[146:147], off
	s_waitcnt lgkmcnt(0)
	s_barrier
	s_waitcnt lgkmcnt(0)
	v_mfma_f32_16x16x32_bf16 v[128:131], v[152:155], v[200:203], 0
	v_mfma_f32_16x16x32_bf16 v[120:123], v[160:163], v[200:203], 0
	v_mfma_f32_16x16x32_bf16 v[112:115], v[152:155], v[208:211], 0
	v_mfma_f32_16x16x32_bf16 v[104:107], v[160:163], v[208:211], 0
	v_mfma_f32_16x16x32_bf16 v[96:99], v[152:155], v[216:219], 0
	v_mfma_f32_16x16x32_bf16 v[88:91], v[160:163], v[216:219], 0
	v_mfma_f32_16x16x32_bf16 v[80:83], v[152:155], v[224:227], 0
	v_mfma_f32_16x16x32_bf16 v[72:75], v[160:163], v[224:227], 0
	v_mfma_f32_16x16x32_bf16 v[128:131], v[156:159], v[204:207], v[128:131]
	v_mfma_f32_16x16x32_bf16 v[120:123], v[168:171], v[204:207], v[120:123]
	v_mfma_f32_16x16x32_bf16 v[112:115], v[156:159], v[212:215], v[112:115]
	v_mfma_f32_16x16x32_bf16 v[104:107], v[168:171], v[212:215], v[104:107]
	v_mfma_f32_16x16x32_bf16 v[96:99], v[156:159], v[220:223], v[96:99]
	v_mfma_f32_16x16x32_bf16 v[88:91], v[168:171], v[220:223], v[88:91]
	v_mfma_f32_16x16x32_bf16 v[80:83], v[156:159], v[228:231], v[80:83]
	v_mfma_f32_16x16x32_bf16 v[72:75], v[168:171], v[228:231], v[72:75]
	v_mfma_f32_16x16x32_bf16 v[124:127], v[174:177], v[200:203], 0
	v_mfma_f32_16x16x32_bf16 v[116:119], v[182:185], v[200:203], 0
	v_mfma_f32_16x16x32_bf16 v[108:111], v[174:177], v[208:211], 0
	v_mfma_f32_16x16x32_bf16 v[100:103], v[182:185], v[208:211], 0
	v_mfma_f32_16x16x32_bf16 v[92:95], v[174:177], v[216:219], 0
	v_mfma_f32_16x16x32_bf16 v[84:87], v[182:185], v[216:219], 0
	v_mfma_f32_16x16x32_bf16 v[76:79], v[174:177], v[224:227], 0
	v_mfma_f32_16x16x32_bf16 v[68:71], v[182:185], v[224:227], 0
	v_mfma_f32_16x16x32_bf16 v[124:127], v[178:181], v[204:207], v[124:127]
	v_mfma_f32_16x16x32_bf16 v[116:119], v[186:189], v[204:207], v[116:119]
	v_mfma_f32_16x16x32_bf16 v[108:111], v[178:181], v[212:215], v[108:111]
	v_mfma_f32_16x16x32_bf16 v[100:103], v[186:189], v[212:215], v[100:103]
	v_mfma_f32_16x16x32_bf16 v[92:95], v[178:181], v[220:223], v[92:95]
	v_mfma_f32_16x16x32_bf16 v[84:87], v[186:189], v[220:223], v[84:87]
	v_mfma_f32_16x16x32_bf16 v[76:79], v[178:181], v[228:231], v[76:79]
	v_mfma_f32_16x16x32_bf16 v[68:71], v[186:189], v[228:231], v[68:71]
	s_waitcnt vmcnt(8)
	s_barrier
	s_add_i32 s33, s82, s20
	v_lshl_add_u64 v[146:147], s[70:71], 0, v[134:135]
	s_mov_b32 m0, s33
	ds_read_b128 v[200:203], v151 offset:16384
	ds_read_b128 v[204:207], v151 offset:17408
	ds_read_b128 v[208:211], v151 offset:18432
	ds_read_b128 v[212:215], v151 offset:19456
	ds_read_b128 v[216:219], v151 offset:20480
	ds_read_b128 v[220:223], v151 offset:21504
	ds_read_b128 v[224:227], v151 offset:22528
	ds_read_b128 v[228:231], v151 offset:23552
	global_load_lds_dwordx4 v[146:147], off
	s_add_i32 m0, s33, 0x2000
	s_add_u32 s82, s70, 0x40000
	v_lshl_add_u64 v[164:165], s[70:71], 0, v[138:139]
	s_addc_u32 s83, s71, 0
	s_add_i32 s6, s6, s20
	global_load_lds_dwordx4 v[164:165], off
	v_lshl_add_u64 v[232:233], s[82:83], 0, v[134:135]
	s_mov_b32 m0, s6
	v_lshl_add_u64 v[234:235], s[72:73], 0, v[136:137]
	global_load_lds_dwordx4 v[232:233], off
	v_lshl_add_u64 v[232:233], s[82:83], 0, v[138:139]
	s_add_i32 m0, s6, 0x2000
	s_nop 0
	global_load_lds_dwordx4 v[232:233], off
	v_lshl_add_u64 v[232:233], s[72:73], 0, v[132:133]
	s_mov_b32 m0, s35
	s_nop 0
	global_load_lds_dwordx4 v[232:233], off
	s_mov_b32 m0, s54
	s_nop 0
	global_load_lds_dwordx4 v[234:235], off
	s_waitcnt lgkmcnt(0)
	s_barrier
	s_waitcnt lgkmcnt(0)
	v_mfma_f32_16x16x32_bf16 v[64:67], v[152:155], v[200:203], 0
	v_mfma_f32_16x16x32_bf16 v[56:59], v[160:163], v[200:203], 0
	v_mfma_f32_16x16x32_bf16 v[48:51], v[152:155], v[208:211], 0
	v_mfma_f32_16x16x32_bf16 v[40:43], v[160:163], v[208:211], 0
	v_mfma_f32_16x16x32_bf16 v[32:35], v[152:155], v[216:219], 0
	v_mfma_f32_16x16x32_bf16 v[24:27], v[160:163], v[216:219], 0
	v_mfma_f32_16x16x32_bf16 v[16:19], v[152:155], v[224:227], 0
	v_mfma_f32_16x16x32_bf16 v[8:11], v[160:163], v[224:227], 0
	v_mfma_f32_16x16x32_bf16 v[64:67], v[156:159], v[204:207], v[64:67]
	v_mfma_f32_16x16x32_bf16 v[56:59], v[168:171], v[204:207], v[56:59]
	v_mfma_f32_16x16x32_bf16 v[48:51], v[156:159], v[212:215], v[48:51]
	v_mfma_f32_16x16x32_bf16 v[40:43], v[168:171], v[212:215], v[40:43]
	v_mfma_f32_16x16x32_bf16 v[32:35], v[156:159], v[220:223], v[32:35]
	v_mfma_f32_16x16x32_bf16 v[24:27], v[168:171], v[220:223], v[24:27]
	v_mfma_f32_16x16x32_bf16 v[16:19], v[156:159], v[228:231], v[16:19]
	v_mfma_f32_16x16x32_bf16 v[8:11], v[168:171], v[228:231], v[8:11]
	v_mfma_f32_16x16x32_bf16 v[60:63], v[174:177], v[200:203], 0
	v_mfma_f32_16x16x32_bf16 v[52:55], v[182:185], v[200:203], 0
	v_mfma_f32_16x16x32_bf16 v[44:47], v[174:177], v[208:211], 0
	v_mfma_f32_16x16x32_bf16 v[36:39], v[182:185], v[208:211], 0
	v_mfma_f32_16x16x32_bf16 v[28:31], v[174:177], v[216:219], 0
	v_mfma_f32_16x16x32_bf16 v[20:23], v[182:185], v[216:219], 0
	v_mfma_f32_16x16x32_bf16 v[12:15], v[174:177], v[224:227], 0
	v_mfma_f32_16x16x32_bf16 v[4:7], v[182:185], v[224:227], 0
	v_mfma_f32_16x16x32_bf16 v[60:63], v[178:181], v[204:207], v[60:63]
	v_mfma_f32_16x16x32_bf16 v[52:55], v[186:189], v[204:207], v[52:55]
	v_mfma_f32_16x16x32_bf16 v[44:47], v[178:181], v[212:215], v[44:47]
	v_mfma_f32_16x16x32_bf16 v[36:39], v[186:189], v[212:215], v[36:39]
	v_mfma_f32_16x16x32_bf16 v[28:31], v[178:181], v[220:223], v[28:31]
	v_mfma_f32_16x16x32_bf16 v[20:23], v[186:189], v[220:223], v[20:23]
	v_mfma_f32_16x16x32_bf16 v[12:15], v[178:181], v[228:231], v[12:15]
	v_mfma_f32_16x16x32_bf16 v[4:7], v[186:189], v[228:231], v[4:7]
	s_waitcnt vmcnt(8)
	s_barrier
	s_add_i32 s6, 0, 0x18000
	v_add_u32_e32 v2, s6, v148
	s_add_i32 s33, 0, 0x1c000
	ds_read_b128 v[152:155], v2
	ds_read_b128 v[156:159], v2 offset:1024
	ds_read_b128 v[160:163], v2 offset:2048
	ds_read_b128 v[168:171], v2 offset:3072
	v_add_u32_e32 v2, s33, v148
	ds_read_b128 v[174:177], v2
	ds_read_b128 v[178:181], v2 offset:1024
	ds_read_b128 v[182:185], v2 offset:2048
	ds_read_b128 v[186:189], v2 offset:3072
	s_add_u32 s72, s72, 0x40000
	s_addc_u32 s73, s73, 0
	s_mov_b32 m0, s55
	v_lshl_add_u64 v[236:237], s[72:73], 0, v[132:133]
	ds_read_b128 v[200:203], v151 offset:32768
	ds_read_b128 v[204:207], v151 offset:33792
	ds_read_b128 v[208:211], v151 offset:34816
	ds_read_b128 v[212:215], v151 offset:35840
	ds_read_b128 v[216:219], v151 offset:36864
	ds_read_b128 v[220:223], v151 offset:37888
	ds_read_b128 v[224:227], v151 offset:38912
	ds_read_b128 v[228:231], v151 offset:39936
	global_load_lds_dwordx4 v[236:237], off
	v_lshl_add_u64 v[236:237], s[72:73], 0, v[136:137]
	s_mov_b32 m0, s56
	s_nop 0
	global_load_lds_dwordx4 v[236:237], off
	s_waitcnt lgkmcnt(0)
	s_barrier
	s_waitcnt lgkmcnt(0)
	v_mfma_f32_16x16x32_bf16 v[128:131], v[152:155], v[200:203], v[128:131]
	v_mfma_f32_16x16x32_bf16 v[120:123], v[160:163], v[200:203], v[120:123]
	v_mfma_f32_16x16x32_bf16 v[112:115], v[152:155], v[208:211], v[112:115]
	v_mfma_f32_16x16x32_bf16 v[104:107], v[160:163], v[208:211], v[104:107]
	v_mfma_f32_16x16x32_bf16 v[96:99], v[152:155], v[216:219], v[96:99]
	v_mfma_f32_16x16x32_bf16 v[88:91], v[160:163], v[216:219], v[88:91]
	v_mfma_f32_16x16x32_bf16 v[80:83], v[152:155], v[224:227], v[80:83]
	v_mfma_f32_16x16x32_bf16 v[72:75], v[160:163], v[224:227], v[72:75]
	v_mfma_f32_16x16x32_bf16 v[128:131], v[156:159], v[204:207], v[128:131]
	v_mfma_f32_16x16x32_bf16 v[120:123], v[168:171], v[204:207], v[120:123]
	v_mfma_f32_16x16x32_bf16 v[112:115], v[156:159], v[212:215], v[112:115]
	v_mfma_f32_16x16x32_bf16 v[104:107], v[168:171], v[212:215], v[104:107]
	v_mfma_f32_16x16x32_bf16 v[96:99], v[156:159], v[220:223], v[96:99]
	v_mfma_f32_16x16x32_bf16 v[88:91], v[168:171], v[220:223], v[88:91]
	v_mfma_f32_16x16x32_bf16 v[80:83], v[156:159], v[228:231], v[80:83]
	v_mfma_f32_16x16x32_bf16 v[72:75], v[168:171], v[228:231], v[72:75]
	v_mfma_f32_16x16x32_bf16 v[124:127], v[174:177], v[200:203], v[124:127]
	v_mfma_f32_16x16x32_bf16 v[116:119], v[182:185], v[200:203], v[116:119]
	v_mfma_f32_16x16x32_bf16 v[108:111], v[174:177], v[208:211], v[108:111]
	v_mfma_f32_16x16x32_bf16 v[100:103], v[182:185], v[208:211], v[100:103]
	v_mfma_f32_16x16x32_bf16 v[92:95], v[174:177], v[216:219], v[92:95]
	v_mfma_f32_16x16x32_bf16 v[84:87], v[182:185], v[216:219], v[84:87]
	v_mfma_f32_16x16x32_bf16 v[76:79], v[174:177], v[224:227], v[76:79]
	v_mfma_f32_16x16x32_bf16 v[68:71], v[182:185], v[224:227], v[68:71]
	v_mfma_f32_16x16x32_bf16 v[124:127], v[178:181], v[204:207], v[124:127]
	v_mfma_f32_16x16x32_bf16 v[116:119], v[186:189], v[204:207], v[116:119]
	v_mfma_f32_16x16x32_bf16 v[108:111], v[178:181], v[212:215], v[108:111]
	v_mfma_f32_16x16x32_bf16 v[100:103], v[186:189], v[212:215], v[100:103]
	v_mfma_f32_16x16x32_bf16 v[92:95], v[178:181], v[220:223], v[92:95]
	v_mfma_f32_16x16x32_bf16 v[84:87], v[186:189], v[220:223], v[84:87]
	v_mfma_f32_16x16x32_bf16 v[76:79], v[178:181], v[228:231], v[76:79]
	v_mfma_f32_16x16x32_bf16 v[68:71], v[186:189], v[228:231], v[68:71]
	s_waitcnt vmcnt(8)
	s_barrier
	s_add_i32 s6, s6, s20
	v_lshl_add_u64 v[146:147], v[146:147], 0, s[30:31]
	s_mov_b32 m0, s6
	ds_read_b128 v[200:203], v151 offset:49152
	ds_read_b128 v[204:207], v151 offset:50176
	ds_read_b128 v[208:211], v151 offset:51200
	ds_read_b128 v[212:215], v151 offset:52224
	ds_read_b128 v[216:219], v151 offset:53248
	ds_read_b128 v[220:223], v151 offset:54272
	ds_read_b128 v[224:227], v151 offset:55296
	ds_read_b128 v[228:231], v151 offset:56320
	global_load_lds_dwordx4 v[146:147], off
	s_add_i32 m0, s6, 0x2000
	s_add_u32 s70, s70, 0x40080
	v_lshl_add_u64 v[146:147], v[164:165], 0, s[30:31]
	s_addc_u32 s71, s71, 0
	s_add_i32 s6, s33, s20
	global_load_lds_dwordx4 v[146:147], off
	v_lshl_add_u64 v[146:147], s[70:71], 0, v[134:135]
	s_mov_b32 m0, s6
	s_nop 0
	global_load_lds_dwordx4 v[146:147], off
	v_lshl_add_u64 v[146:147], s[70:71], 0, v[138:139]
	s_add_i32 m0, s6, 0x2000
	s_nop 0
	global_load_lds_dwordx4 v[146:147], off
	v_lshl_add_u64 v[146:147], v[232:233], 0, s[30:31]
	s_mov_b32 m0, s76
	s_nop 0
	global_load_lds_dwordx4 v[146:147], off
	v_lshl_add_u64 v[146:147], v[234:235], 0, s[30:31]
	s_mov_b32 m0, s77
	s_nop 0
	global_load_lds_dwordx4 v[146:147], off
	s_waitcnt lgkmcnt(0)
	s_barrier
	s_waitcnt lgkmcnt(0)
	v_mfma_f32_16x16x32_bf16 v[64:67], v[152:155], v[200:203], v[64:67]
	v_mfma_f32_16x16x32_bf16 v[56:59], v[160:163], v[200:203], v[56:59]
	v_mfma_f32_16x16x32_bf16 v[48:51], v[152:155], v[208:211], v[48:51]
	v_mfma_f32_16x16x32_bf16 v[40:43], v[160:163], v[208:211], v[40:43]
	v_mfma_f32_16x16x32_bf16 v[32:35], v[152:155], v[216:219], v[32:35]
	v_mfma_f32_16x16x32_bf16 v[24:27], v[160:163], v[216:219], v[24:27]
	v_mfma_f32_16x16x32_bf16 v[16:19], v[152:155], v[224:227], v[16:19]
	v_mfma_f32_16x16x32_bf16 v[8:11], v[160:163], v[224:227], v[8:11]
	v_mfma_f32_16x16x32_bf16 v[64:67], v[156:159], v[204:207], v[64:67]
	v_mfma_f32_16x16x32_bf16 v[56:59], v[168:171], v[204:207], v[56:59]
	v_mfma_f32_16x16x32_bf16 v[48:51], v[156:159], v[212:215], v[48:51]
	v_mfma_f32_16x16x32_bf16 v[40:43], v[168:171], v[212:215], v[40:43]
	v_mfma_f32_16x16x32_bf16 v[32:35], v[156:159], v[220:223], v[32:35]
	v_mfma_f32_16x16x32_bf16 v[24:27], v[168:171], v[220:223], v[24:27]
	v_mfma_f32_16x16x32_bf16 v[16:19], v[156:159], v[228:231], v[16:19]
	v_mfma_f32_16x16x32_bf16 v[8:11], v[168:171], v[228:231], v[8:11]
	v_mfma_f32_16x16x32_bf16 v[60:63], v[174:177], v[200:203], v[60:63]
	v_mfma_f32_16x16x32_bf16 v[52:55], v[182:185], v[200:203], v[52:55]
	v_mfma_f32_16x16x32_bf16 v[44:47], v[174:177], v[208:211], v[44:47]
	v_mfma_f32_16x16x32_bf16 v[36:39], v[182:185], v[208:211], v[36:39]
	v_mfma_f32_16x16x32_bf16 v[28:31], v[174:177], v[216:219], v[28:31]
	v_mfma_f32_16x16x32_bf16 v[20:23], v[182:185], v[216:219], v[20:23]
	v_mfma_f32_16x16x32_bf16 v[12:15], v[174:177], v[224:227], v[12:15]
	v_mfma_f32_16x16x32_bf16 v[4:7], v[182:185], v[224:227], v[4:7]
	v_mfma_f32_16x16x32_bf16 v[60:63], v[178:181], v[204:207], v[60:63]
	v_mfma_f32_16x16x32_bf16 v[52:55], v[186:189], v[204:207], v[52:55]
	v_mfma_f32_16x16x32_bf16 v[44:47], v[178:181], v[212:215], v[44:47]
	v_mfma_f32_16x16x32_bf16 v[36:39], v[186:189], v[212:215], v[36:39]
	v_mfma_f32_16x16x32_bf16 v[28:31], v[178:181], v[220:223], v[28:31]
	v_mfma_f32_16x16x32_bf16 v[20:23], v[186:189], v[220:223], v[20:23]
	v_mfma_f32_16x16x32_bf16 v[12:15], v[178:181], v[228:231], v[12:15]
	v_mfma_f32_16x16x32_bf16 v[4:7], v[186:189], v[228:231], v[4:7]
	s_waitcnt vmcnt(8)
	s_barrier
	s_add_i32 s80, s80, 2
	s_add_u32 s68, s68, 0x100
	s_addc_u32 s69, s69, 0
	s_add_u32 s61, s61, 0x100
	s_addc_u32 s67, s67, 0
.Llw4_loop:
	s_add_u32 s6, s68, 0xfffc0080
	s_addc_u32 s33, s69, -1
	s_add_i32 s82, 0, 0x10000
	s_cmp_eq_u32 s80, 12
	s_cselect_b32 s73, s10, s33
	s_cselect_b32 s72, s11, s6
	v_add_u32_e32 v2, s82, v148
	s_cselect_b32 s71, s15, s67
	s_cselect_b32 s70, s59, s61
	s_add_i32 s6, 0, 0x14000
	ds_read_b128 v[152:155], v2
	ds_read_b128 v[156:159], v2 offset:1024
	ds_read_b128 v[160:163], v2 offset:2048
	ds_read_b128 v[168:171], v2 offset:3072
	v_add_u32_e32 v2, s6, v148
	ds_read_b128 v[174:177], v2
	ds_read_b128 v[178:181], v2 offset:1024
	ds_read_b128 v[182:185], v2 offset:2048
	ds_read_b128 v[186:189], v2 offset:3072
	v_lshl_add_u64 v[146:147], s[68:69], 0, v[142:143]
	s_add_i32 m0, s35, 0xc000
	ds_read_b128 v[200:203], v151
	ds_read_b128 v[204:207], v151 offset:1024
	ds_read_b128 v[208:211], v151 offset:2048
	ds_read_b128 v[212:215], v151 offset:3072
	ds_read_b128 v[216:219], v151 offset:4096
	ds_read_b128 v[220:223], v151 offset:5120
	ds_read_b128 v[224:227], v151 offset:6144
	ds_read_b128 v[228:231], v151 offset:7168
	global_load_lds_dwordx4 v[146:147], off
	v_lshl_add_u64 v[146:147], s[68:69], 0, v[144:145]
	s_add_i32 m0, s35, 0xe000
	s_nop 0
	global_load_lds_dwordx4 v[146:147], off
	s_waitcnt lgkmcnt(0)
	s_barrier
	s_waitcnt lgkmcnt(0)
	v_mfma_f32_16x16x32_bf16 v[128:131], v[152:155], v[200:203], v[128:131]
	v_mfma_f32_16x16x32_bf16 v[120:123], v[160:163], v[200:203], v[120:123]
	v_mfma_f32_16x16x32_bf16 v[112:115], v[152:155], v[208:211], v[112:115]
	v_mfma_f32_16x16x32_bf16 v[104:107], v[160:163], v[208:211], v[104:107]
	v_mfma_f32_16x16x32_bf16 v[96:99], v[152:155], v[216:219], v[96:99]
	v_mfma_f32_16x16x32_bf16 v[88:91], v[160:163], v[216:219], v[88:91]
	v_mfma_f32_16x16x32_bf16 v[80:83], v[152:155], v[224:227], v[80:83]
	v_mfma_f32_16x16x32_bf16 v[72:75], v[160:163], v[224:227], v[72:75]
	v_mfma_f32_16x16x32_bf16 v[128:131], v[156:159], v[204:207], v[128:131]
	v_mfma_f32_16x16x32_bf16 v[120:123], v[168:171], v[204:207], v[120:123]
	v_mfma_f32_16x16x32_bf16 v[112:115], v[156:159], v[212:215], v[112:115]
	v_mfma_f32_16x16x32_bf16 v[104:107], v[168:171], v[212:215], v[104:107]
	v_mfma_f32_16x16x32_bf16 v[96:99], v[156:159], v[220:223], v[96:99]
	v_mfma_f32_16x16x32_bf16 v[88:91], v[168:171], v[220:223], v[88:91]
	v_mfma_f32_16x16x32_bf16 v[80:83], v[156:159], v[228:231], v[80:83]
	v_mfma_f32_16x16x32_bf16 v[72:75], v[168:171], v[228:231], v[72:75]
	v_mfma_f32_16x16x32_bf16 v[124:127], v[174:177], v[200:203], v[124:127]
	v_mfma_f32_16x16x32_bf16 v[116:119], v[182:185], v[200:203], v[116:119]
	v_mfma_f32_16x16x32_bf16 v[108:111], v[174:177], v[208:211], v[108:111]
	v_mfma_f32_16x16x32_bf16 v[100:103], v[182:185], v[208:211], v[100:103]
	v_mfma_f32_16x16x32_bf16 v[92:95], v[174:177], v[216:219], v[92:95]
	v_mfma_f32_16x16x32_bf16 v[84:87], v[182:185], v[216:219], v[84:87]
	v_mfma_f32_16x16x32_bf16 v[76:79], v[174:177], v[224:227], v[76:79]
	v_mfma_f32_16x16x32_bf16 v[68:71], v[182:185], v[224:227], v[68:71]
	v_mfma_f32_16x16x32_bf16 v[124:127], v[178:181], v[204:207], v[124:127]
	v_mfma_f32_16x16x32_bf16 v[116:119], v[186:189], v[204:207], v[116:119]
	v_mfma_f32_16x16x32_bf16 v[108:111], v[178:181], v[212:215], v[108:111]
	v_mfma_f32_16x16x32_bf16 v[100:103], v[186:189], v[212:215], v[100:103]
	v_mfma_f32_16x16x32_bf16 v[92:95], v[178:181], v[220:223], v[92:95]
	v_mfma_f32_16x16x32_bf16 v[84:87], v[186:189], v[220:223], v[84:87]
	v_mfma_f32_16x16x32_bf16 v[76:79], v[178:181], v[228:231], v[76:79]
	v_mfma_f32_16x16x32_bf16 v[68:71], v[186:189], v[228:231], v[68:71]
	s_waitcnt vmcnt(8)
	s_barrier
	s_add_i32 s33, s82, s20
	v_lshl_add_u64 v[146:147], s[70:71], 0, v[134:135]
	s_mov_b32 m0, s33
	ds_read_b128 v[200:203], v151 offset:16384
	ds_read_b128 v[204:207], v151 offset:17408
	ds_read_b128 v[208:211], v151 offset:18432
	ds_read_b128 v[212:215], v151 offset:19456
	ds_read_b128 v[216:219], v151 offset:20480
	ds_read_b128 v[220:223], v151 offset:21504
	ds_read_b128 v[224:227], v151 offset:22528
	ds_read_b128 v[228:231], v151 offset:23552
	global_load_lds_dwordx4 v[146:147], off
	s_add_i32 m0, s33, 0x2000
	s_add_u32 s82, s70, 0x40000
	v_lshl_add_u64 v[164:165], s[70:71], 0, v[138:139]
	s_addc_u32 s83, s71, 0
	s_add_i32 s6, s6, s20
	global_load_lds_dwordx4 v[164:165], off
	v_lshl_add_u64 v[232:233], s[82:83], 0, v[134:135]
	s_mov_b32 m0, s6
	v_lshl_add_u64 v[234:235], s[72:73], 0, v[136:137]
	global_load_lds_dwordx4 v[232:233], off
	v_lshl_add_u64 v[232:233], s[82:83], 0, v[138:139]
	s_add_i32 m0, s6, 0x2000
	s_nop 0
	global_load_lds_dwordx4 v[232:233], off
	v_lshl_add_u64 v[232:233], s[72:73], 0, v[132:133]
	s_mov_b32 m0, s35
	s_nop 0
	global_load_lds_dwordx4 v[232:233], off
	s_mov_b32 m0, s54
	s_nop 0
	global_load_lds_dwordx4 v[234:235], off
	s_waitcnt lgkmcnt(0)
	s_barrier
	s_waitcnt lgkmcnt(0)
	v_mfma_f32_16x16x32_bf16 v[64:67], v[152:155], v[200:203], v[64:67]
	v_mfma_f32_16x16x32_bf16 v[56:59], v[160:163], v[200:203], v[56:59]
	v_mfma_f32_16x16x32_bf16 v[48:51], v[152:155], v[208:211], v[48:51]
	v_mfma_f32_16x16x32_bf16 v[40:43], v[160:163], v[208:211], v[40:43]
	v_mfma_f32_16x16x32_bf16 v[32:35], v[152:155], v[216:219], v[32:35]
	v_mfma_f32_16x16x32_bf16 v[24:27], v[160:163], v[216:219], v[24:27]
	v_mfma_f32_16x16x32_bf16 v[16:19], v[152:155], v[224:227], v[16:19]
	v_mfma_f32_16x16x32_bf16 v[8:11], v[160:163], v[224:227], v[8:11]
	v_mfma_f32_16x16x32_bf16 v[64:67], v[156:159], v[204:207], v[64:67]
	v_mfma_f32_16x16x32_bf16 v[56:59], v[168:171], v[204:207], v[56:59]
	v_mfma_f32_16x16x32_bf16 v[48:51], v[156:159], v[212:215], v[48:51]
	v_mfma_f32_16x16x32_bf16 v[40:43], v[168:171], v[212:215], v[40:43]
	v_mfma_f32_16x16x32_bf16 v[32:35], v[156:159], v[220:223], v[32:35]
	v_mfma_f32_16x16x32_bf16 v[24:27], v[168:171], v[220:223], v[24:27]
	v_mfma_f32_16x16x32_bf16 v[16:19], v[156:159], v[228:231], v[16:19]
	v_mfma_f32_16x16x32_bf16 v[8:11], v[168:171], v[228:231], v[8:11]
	v_mfma_f32_16x16x32_bf16 v[60:63], v[174:177], v[200:203], v[60:63]
	v_mfma_f32_16x16x32_bf16 v[52:55], v[182:185], v[200:203], v[52:55]
	v_mfma_f32_16x16x32_bf16 v[44:47], v[174:177], v[208:211], v[44:47]
	v_mfma_f32_16x16x32_bf16 v[36:39], v[182:185], v[208:211], v[36:39]
	v_mfma_f32_16x16x32_bf16 v[28:31], v[174:177], v[216:219], v[28:31]
	v_mfma_f32_16x16x32_bf16 v[20:23], v[182:185], v[216:219], v[20:23]
	v_mfma_f32_16x16x32_bf16 v[12:15], v[174:177], v[224:227], v[12:15]
	v_mfma_f32_16x16x32_bf16 v[4:7], v[182:185], v[224:227], v[4:7]
	v_mfma_f32_16x16x32_bf16 v[60:63], v[178:181], v[204:207], v[60:63]
	v_mfma_f32_16x16x32_bf16 v[52:55], v[186:189], v[204:207], v[52:55]
	v_mfma_f32_16x16x32_bf16 v[44:47], v[178:181], v[212:215], v[44:47]
	v_mfma_f32_16x16x32_bf16 v[36:39], v[186:189], v[212:215], v[36:39]
	v_mfma_f32_16x16x32_bf16 v[28:31], v[178:181], v[220:223], v[28:31]
	v_mfma_f32_16x16x32_bf16 v[20:23], v[186:189], v[220:223], v[20:23]
	v_mfma_f32_16x16x32_bf16 v[12:15], v[178:181], v[228:231], v[12:15]
	v_mfma_f32_16x16x32_bf16 v[4:7], v[186:189], v[228:231], v[4:7]
	s_waitcnt vmcnt(8)
	s_barrier
	s_add_i32 s6, 0, 0x18000
	v_add_u32_e32 v2, s6, v148
	s_add_i32 s33, 0, 0x1c000
	ds_read_b128 v[152:155], v2
	ds_read_b128 v[156:159], v2 offset:1024
	ds_read_b128 v[160:163], v2 offset:2048
	ds_read_b128 v[168:171], v2 offset:3072
	v_add_u32_e32 v2, s33, v148
	ds_read_b128 v[174:177], v2
	ds_read_b128 v[178:181], v2 offset:1024
	ds_read_b128 v[182:185], v2 offset:2048
	ds_read_b128 v[186:189], v2 offset:3072
	s_add_u32 s72, s72, 0x40000
	s_addc_u32 s73, s73, 0
	s_mov_b32 m0, s55
	v_lshl_add_u64 v[236:237], s[72:73], 0, v[132:133]
	ds_read_b128 v[200:203], v151 offset:32768
	ds_read_b128 v[204:207], v151 offset:33792
	ds_read_b128 v[208:211], v151 offset:34816
	ds_read_b128 v[212:215], v151 offset:35840
	ds_read_b128 v[216:219], v151 offset:36864
	ds_read_b128 v[220:223], v151 offset:37888
	ds_read_b128 v[224:227], v151 offset:38912
	ds_read_b128 v[228:231], v151 offset:39936
	global_load_lds_dwordx4 v[236:237], off
	v_lshl_add_u64 v[236:237], s[72:73], 0, v[136:137]
	s_mov_b32 m0, s56
	s_nop 0
	global_load_lds_dwordx4 v[236:237], off
	s_waitcnt lgkmcnt(0)
	s_barrier
	s_waitcnt lgkmcnt(0)
	v_mfma_f32_16x16x32_bf16 v[128:131], v[152:155], v[200:203], v[128:131]
	v_mfma_f32_16x16x32_bf16 v[120:123], v[160:163], v[200:203], v[120:123]
	v_mfma_f32_16x16x32_bf16 v[112:115], v[152:155], v[208:211], v[112:115]
	v_mfma_f32_16x16x32_bf16 v[104:107], v[160:163], v[208:211], v[104:107]
	v_mfma_f32_16x16x32_bf16 v[96:99], v[152:155], v[216:219], v[96:99]
	v_mfma_f32_16x16x32_bf16 v[88:91], v[160:163], v[216:219], v[88:91]
	v_mfma_f32_16x16x32_bf16 v[80:83], v[152:155], v[224:227], v[80:83]
	v_mfma_f32_16x16x32_bf16 v[72:75], v[160:163], v[224:227], v[72:75]
	v_mfma_f32_16x16x32_bf16 v[128:131], v[156:159], v[204:207], v[128:131]
	v_mfma_f32_16x16x32_bf16 v[120:123], v[168:171], v[204:207], v[120:123]
	v_mfma_f32_16x16x32_bf16 v[112:115], v[156:159], v[212:215], v[112:115]
	v_mfma_f32_16x16x32_bf16 v[104:107], v[168:171], v[212:215], v[104:107]
	v_mfma_f32_16x16x32_bf16 v[96:99], v[156:159], v[220:223], v[96:99]
	v_mfma_f32_16x16x32_bf16 v[88:91], v[168:171], v[220:223], v[88:91]
	v_mfma_f32_16x16x32_bf16 v[80:83], v[156:159], v[228:231], v[80:83]
	v_mfma_f32_16x16x32_bf16 v[72:75], v[168:171], v[228:231], v[72:75]
	v_mfma_f32_16x16x32_bf16 v[124:127], v[174:177], v[200:203], v[124:127]
	v_mfma_f32_16x16x32_bf16 v[116:119], v[182:185], v[200:203], v[116:119]
	v_mfma_f32_16x16x32_bf16 v[108:111], v[174:177], v[208:211], v[108:111]
	v_mfma_f32_16x16x32_bf16 v[100:103], v[182:185], v[208:211], v[100:103]
	v_mfma_f32_16x16x32_bf16 v[92:95], v[174:177], v[216:219], v[92:95]
	v_mfma_f32_16x16x32_bf16 v[84:87], v[182:185], v[216:219], v[84:87]
	v_mfma_f32_16x16x32_bf16 v[76:79], v[174:177], v[224:227], v[76:79]
	v_mfma_f32_16x16x32_bf16 v[68:71], v[182:185], v[224:227], v[68:71]
	v_mfma_f32_16x16x32_bf16 v[124:127], v[178:181], v[204:207], v[124:127]
	v_mfma_f32_16x16x32_bf16 v[116:119], v[186:189], v[204:207], v[116:119]
	v_mfma_f32_16x16x32_bf16 v[108:111], v[178:181], v[212:215], v[108:111]
	v_mfma_f32_16x16x32_bf16 v[100:103], v[186:189], v[212:215], v[100:103]
	v_mfma_f32_16x16x32_bf16 v[92:95], v[178:181], v[220:223], v[92:95]
	v_mfma_f32_16x16x32_bf16 v[84:87], v[186:189], v[220:223], v[84:87]
	v_mfma_f32_16x16x32_bf16 v[76:79], v[178:181], v[228:231], v[76:79]
	v_mfma_f32_16x16x32_bf16 v[68:71], v[186:189], v[228:231], v[68:71]
	s_waitcnt vmcnt(8)
	s_barrier
	s_add_i32 s6, s6, s20
	v_lshl_add_u64 v[146:147], v[146:147], 0, s[30:31]
	s_mov_b32 m0, s6
	ds_read_b128 v[200:203], v151 offset:49152
	ds_read_b128 v[204:207], v151 offset:50176
	ds_read_b128 v[208:211], v151 offset:51200
	ds_read_b128 v[212:215], v151 offset:52224
	ds_read_b128 v[216:219], v151 offset:53248
	ds_read_b128 v[220:223], v151 offset:54272
	ds_read_b128 v[224:227], v151 offset:55296
	ds_read_b128 v[228:231], v151 offset:56320
	global_load_lds_dwordx4 v[146:147], off
	s_add_i32 m0, s6, 0x2000
	s_add_u32 s70, s70, 0x40080
	v_lshl_add_u64 v[146:147], v[164:165], 0, s[30:31]
	s_addc_u32 s71, s71, 0
	s_add_i32 s6, s33, s20
	global_load_lds_dwordx4 v[146:147], off
	v_lshl_add_u64 v[146:147], s[70:71], 0, v[134:135]
	s_mov_b32 m0, s6
	s_nop 0
	global_load_lds_dwordx4 v[146:147], off
	v_lshl_add_u64 v[146:147], s[70:71], 0, v[138:139]
	s_add_i32 m0, s6, 0x2000
	s_nop 0
	global_load_lds_dwordx4 v[146:147], off
	v_lshl_add_u64 v[146:147], v[232:233], 0, s[30:31]
	s_mov_b32 m0, s76
	s_nop 0
	global_load_lds_dwordx4 v[146:147], off
	v_lshl_add_u64 v[146:147], v[234:235], 0, s[30:31]
	s_mov_b32 m0, s77
	s_nop 0
	global_load_lds_dwordx4 v[146:147], off
	s_waitcnt lgkmcnt(0)
	s_barrier
	s_waitcnt lgkmcnt(0)
	v_mfma_f32_16x16x32_bf16 v[64:67], v[152:155], v[200:203], v[64:67]
	v_mfma_f32_16x16x32_bf16 v[56:59], v[160:163], v[200:203], v[56:59]
	v_mfma_f32_16x16x32_bf16 v[48:51], v[152:155], v[208:211], v[48:51]
	v_mfma_f32_16x16x32_bf16 v[40:43], v[160:163], v[208:211], v[40:43]
	v_mfma_f32_16x16x32_bf16 v[32:35], v[152:155], v[216:219], v[32:35]
	v_mfma_f32_16x16x32_bf16 v[24:27], v[160:163], v[216:219], v[24:27]
	v_mfma_f32_16x16x32_bf16 v[16:19], v[152:155], v[224:227], v[16:19]
	v_mfma_f32_16x16x32_bf16 v[8:11], v[160:163], v[224:227], v[8:11]
	v_mfma_f32_16x16x32_bf16 v[64:67], v[156:159], v[204:207], v[64:67]
	v_mfma_f32_16x16x32_bf16 v[56:59], v[168:171], v[204:207], v[56:59]
	v_mfma_f32_16x16x32_bf16 v[48:51], v[156:159], v[212:215], v[48:51]
	v_mfma_f32_16x16x32_bf16 v[40:43], v[168:171], v[212:215], v[40:43]
	v_mfma_f32_16x16x32_bf16 v[32:35], v[156:159], v[220:223], v[32:35]
	v_mfma_f32_16x16x32_bf16 v[24:27], v[168:171], v[220:223], v[24:27]
	v_mfma_f32_16x16x32_bf16 v[16:19], v[156:159], v[228:231], v[16:19]
	v_mfma_f32_16x16x32_bf16 v[8:11], v[168:171], v[228:231], v[8:11]
	v_mfma_f32_16x16x32_bf16 v[60:63], v[174:177], v[200:203], v[60:63]
	v_mfma_f32_16x16x32_bf16 v[52:55], v[182:185], v[200:203], v[52:55]
	v_mfma_f32_16x16x32_bf16 v[44:47], v[174:177], v[208:211], v[44:47]
	v_mfma_f32_16x16x32_bf16 v[36:39], v[182:185], v[208:211], v[36:39]
	v_mfma_f32_16x16x32_bf16 v[28:31], v[174:177], v[216:219], v[28:31]
	v_mfma_f32_16x16x32_bf16 v[20:23], v[182:185], v[216:219], v[20:23]
	v_mfma_f32_16x16x32_bf16 v[12:15], v[174:177], v[224:227], v[12:15]
	v_mfma_f32_16x16x32_bf16 v[4:7], v[182:185], v[224:227], v[4:7]
	v_mfma_f32_16x16x32_bf16 v[60:63], v[178:181], v[204:207], v[60:63]
	v_mfma_f32_16x16x32_bf16 v[52:55], v[186:189], v[204:207], v[52:55]
	v_mfma_f32_16x16x32_bf16 v[44:47], v[178:181], v[212:215], v[44:47]
	v_mfma_f32_16x16x32_bf16 v[36:39], v[186:189], v[212:215], v[36:39]
	v_mfma_f32_16x16x32_bf16 v[28:31], v[178:181], v[220:223], v[28:31]
	v_mfma_f32_16x16x32_bf16 v[20:23], v[186:189], v[220:223], v[20:23]
	v_mfma_f32_16x16x32_bf16 v[12:15], v[178:181], v[228:231], v[12:15]
	v_mfma_f32_16x16x32_bf16 v[4:7], v[186:189], v[228:231], v[4:7]
	s_waitcnt vmcnt(8)
	s_barrier
	s_add_i32 s80, s80, 2
	s_add_u32 s68, s68, 0x100
	s_addc_u32 s69, s69, 0
	s_add_u32 s61, s61, 0x100
	s_addc_u32 s67, s67, 0
	s_cmp_gt_u32 s80, 13
	s_cbranch_scc0 .Llw4_loop
	s_branch .Llw4_join
